# nt hint on the once-read f32 weight loads of the bf16 conversion (P0 and LRU pass-1 tail); on top of v27
# speedup vs baseline: 1.0242x; 1.0091x over previous
; #define LAS __attribute__((address_space(3)))
; __device__ __forceinline__ void tr_item32(const float* W, int K, int N, bf16_t* WT, const float* gsc, bool swz, LAS float* scr, int item, int lane) {
;     const int nblk = N / 64, kb = item / nblk, nb = item - kb * nblk, k0 = 32 * kb, n0 = 64 * nb;
;     int rbase = n0;
;     if (swz) { const int half = n0 >= DFF ? 1 : 0, hid = n0 - half * DFF; rbase = 256 * (hid >> 7) + 128 * half + (hid & 127); }
;     const int kr = lane >> 3, n4 = lane & 7;
;     f32x4 v[2][4];
; #pragma unroll
;     for (int hf = 0; hf < 2; ++hf)
; #pragma unroll
;         for (int i = 0; i < 4; ++i) v[hf][i] = *(const f32x4*)(W + (size_t)(k0 + kr + 8 * i) * N + n0 + 32 * hf + 4 * n4);
;     if (gsc) {
; #pragma unroll
;         for (int i = 0; i < 4; ++i) { const float gg = gsc[k0 + kr + 8 * i]; v[0][i] = v[0][i] * gg; v[1][i] = v[1][i] * gg; }
;     }
.LBB0_69:
	s_lshl_b32 s34, s37, 5
	s_ashr_i32 s37, s36, 31
	s_lshl_b64 s[36:37], s[36:37], 2
	v_or_b32_e32 v36, s34, v39
	s_add_u32 s28, s28, s36
	s_addc_u32 s29, s29, s37
	v_ashrrev_i32_e32 v37, 31, v36
	v_or_b32_e32 v4, 8, v36
	v_or_b32_e32 v6, 16, v36
	v_or_b32_e32 v8, 24, v36
	v_lshl_add_u64 v[0:1], s[28:29], 0, v[34:35]
	v_mul_lo_u32 v10, v37, s38
	v_mad_u64_u32 v[2:3], s[28:29], v36, s38, 0
	v_mad_u64_u32 v[4:5], s[28:29], v4, s38, 0
	v_mad_u64_u32 v[6:7], s[28:29], v6, s38, 0
	v_mad_u64_u32 v[8:9], s[28:29], v8, s38, 0
	v_add_u32_e32 v3, v3, v10
	v_add_u32_e32 v5, v5, v10
	v_add_u32_e32 v7, v7, v10
	v_add_u32_e32 v9, v9, v10
	v_lshl_add_u64 v[2:3], v[2:3], 2, v[0:1]
	v_lshl_add_u64 v[4:5], v[4:5], 2, v[0:1]
	v_lshl_add_u64 v[6:7], v[6:7], 2, v[0:1]
	v_lshl_add_u64 v[0:1], v[8:9], 2, v[0:1]
	global_load_dwordx4 v[28:31], v[2:3], off nt
	global_load_dwordx4 v[12:15], v[2:3], off offset:128 nt
	global_load_dwordx4 v[24:27], v[4:5], off nt
	global_load_dwordx4 v[8:11], v[4:5], off offset:128 nt
	global_load_dwordx4 v[20:23], v[6:7], off nt
	s_nop 0
	global_load_dwordx4 v[4:7], v[6:7], off offset:128 nt
	s_nop 0
	global_load_dwordx4 v[16:19], v[0:1], off nt
	s_nop 0
	global_load_dwordx4 v[0:3], v[0:1], off offset:128 nt
	s_cmp_eq_u64 s[30:31], 0
	s_cbranch_scc1 .LBB0_26
	v_lshl_add_u64 v[36:37], v[36:37], 2, s[30:31]
	global_load_dword v44, v[36:37], off
	global_load_dword v46, v[36:37], off offset:32
	global_load_dword v48, v[36:37], off offset:64
	s_nop 0
	global_load_dword v36, v[36:37], off offset:96
	s_waitcnt vmcnt(3)
	v_pk_mul_f32 v[30:31], v[30:31], v[44:45] op_sel_hi:[1,0]
	v_pk_mul_f32 v[28:29], v[28:29], v[44:45] op_sel_hi:[1,0]
	v_pk_mul_f32 v[14:15], v[14:15], v[44:45] op_sel_hi:[1,0]
	v_pk_mul_f32 v[12:13], v[12:13], v[44:45] op_sel_hi:[1,0]
	s_waitcnt vmcnt(2)
	v_pk_mul_f32 v[26:27], v[26:27], v[46:47] op_sel_hi:[1,0]
	v_pk_mul_f32 v[24:25], v[24:25], v[46:47] op_sel_hi:[1,0]
	v_pk_mul_f32 v[10:11], v[10:11], v[46:47] op_sel_hi:[1,0]
	v_pk_mul_f32 v[8:9], v[8:9], v[46:47] op_sel_hi:[1,0]
	s_waitcnt vmcnt(1)
	v_pk_mul_f32 v[22:23], v[22:23], v[48:49] op_sel_hi:[1,0]
	v_pk_mul_f32 v[20:21], v[20:21], v[48:49] op_sel_hi:[1,0]
	v_pk_mul_f32 v[6:7], v[6:7], v[48:49] op_sel_hi:[1,0]
	v_pk_mul_f32 v[4:5], v[4:5], v[48:49] op_sel_hi:[1,0]
	s_waitcnt vmcnt(0)
	v_pk_mul_f32 v[18:19], v[18:19], v[36:37] op_sel_hi:[1,0]
	v_pk_mul_f32 v[16:17], v[16:17], v[36:37] op_sel_hi:[1,0]
	v_pk_mul_f32 v[2:3], v[2:3], v[36:37] op_sel_hi:[1,0]
	v_pk_mul_f32 v[0:1], v[0:1], v[36:37] op_sel_hi:[1,0]
	s_branch .LBB0_26

; #define LAS __attribute__((address_space(3)))
; __device__ __forceinline__ void tr_item32(const float* W, int K, int N, bf16_t* WT, const float* gsc, bool swz, LAS float* scr, int item, int lane) {
;     const int nblk = N / 64, kb = item / nblk, nb = item - kb * nblk, k0 = 32 * kb, n0 = 64 * nb;
;     int rbase = n0;
;     if (swz) { const int half = n0 >= DFF ? 1 : 0, hid = n0 - half * DFF; rbase = 256 * (hid >> 7) + 128 * half + (hid & 127); }
;     const int kr = lane >> 3, n4 = lane & 7;
;     f32x4 v[2][4];
; #pragma unroll
;     for (int hf = 0; hf < 2; ++hf)
; #pragma unroll
;         for (int i = 0; i < 4; ++i) v[hf][i] = *(const f32x4*)(W + (size_t)(k0 + kr + 8 * i) * N + n0 + 32 * hf + 4 * n4);
;     if (gsc) {
; #pragma unroll
;         for (int i = 0; i < 4; ++i) { const float gg = gsc[k0 + kr + 8 * i]; v[0][i] = v[0][i] * gg; v[1][i] = v[1][i] * gg; }
;     }
.LBB0_737:
	s_ashr_i32 s97, s96, 31
	s_lshl_b32 s23, s23, 5
	s_lshl_b64 s[16:17], s[96:97], 2
	v_or_b32_e32 v42, s23, v244
	s_add_u32 s16, s28, s16
	s_addc_u32 s17, s29, s17
	v_or_b32_e32 v14, 8, v42
	v_or_b32_e32 v16, 16, v42
	v_or_b32_e32 v18, 24, v42
	v_lshl_add_u64 v[10:11], s[16:17], 0, v[0:1]
	v_mul_hi_u32_u24_e32 v13, s22, v42
	v_mul_u32_u24_e32 v12, s22, v42
	v_mul_hi_u32_u24_e32 v15, s22, v14
	v_mul_u32_u24_e32 v14, s22, v14
	v_mul_hi_u32_u24_e32 v17, s22, v16
	v_mul_u32_u24_e32 v16, s22, v16
	v_mul_hi_u32_u24_e32 v19, s22, v18
	v_mul_u32_u24_e32 v18, s22, v18
	v_lshl_add_u64 v[12:13], v[12:13], 2, v[10:11]
	v_lshl_add_u64 v[14:15], v[14:15], 2, v[10:11]
	v_lshl_add_u64 v[16:17], v[16:17], 2, v[10:11]
	v_lshl_add_u64 v[10:11], v[18:19], 2, v[10:11]
	global_load_dwordx4 v[38:41], v[12:13], off nt
	global_load_dwordx4 v[22:25], v[12:13], off offset:128 nt
	global_load_dwordx4 v[34:37], v[14:15], off nt
	global_load_dwordx4 v[18:21], v[14:15], off offset:128 nt
	global_load_dwordx4 v[30:33], v[16:17], off nt
	s_nop 0
	global_load_dwordx4 v[14:17], v[16:17], off offset:128 nt
	s_nop 0
	global_load_dwordx4 v[26:29], v[10:11], off nt
	s_nop 0
	global_load_dwordx4 v[10:13], v[10:11], off offset:128 nt
	s_cmp_eq_u64 s[12:13], 0
	s_cbranch_scc1 .LBB0_697
	v_lshlrev_b32_e32 v43, 2, v42
	global_load_dword v42, v43, s[12:13]
	s_waitcnt vmcnt(0)
	v_pk_mul_f32 v[40:41], v[40:41], v[42:43] op_sel_hi:[1,0]
	v_pk_mul_f32 v[38:39], v[38:39], v[42:43] op_sel_hi:[1,0]
	v_pk_mul_f32 v[24:25], v[24:25], v[42:43] op_sel_hi:[1,0]
	v_pk_mul_f32 v[22:23], v[22:23], v[42:43] op_sel_hi:[1,0]
	global_load_dword v42, v43, s[12:13] offset:32
	s_waitcnt vmcnt(0)
	v_pk_mul_f32 v[36:37], v[36:37], v[42:43] op_sel_hi:[1,0]
	v_pk_mul_f32 v[34:35], v[34:35], v[42:43] op_sel_hi:[1,0]
	v_pk_mul_f32 v[20:21], v[20:21], v[42:43] op_sel_hi:[1,0]
	v_pk_mul_f32 v[18:19], v[18:19], v[42:43] op_sel_hi:[1,0]
	global_load_dword v42, v43, s[12:13] offset:64
	s_waitcnt vmcnt(0)
	v_pk_mul_f32 v[32:33], v[32:33], v[42:43] op_sel_hi:[1,0]
	v_pk_mul_f32 v[30:31], v[30:31], v[42:43] op_sel_hi:[1,0]
	v_pk_mul_f32 v[16:17], v[16:17], v[42:43] op_sel_hi:[1,0]
	v_pk_mul_f32 v[14:15], v[14:15], v[42:43] op_sel_hi:[1,0]
	global_load_dword v42, v43, s[12:13] offset:96
	s_waitcnt vmcnt(0)
	v_pk_mul_f32 v[28:29], v[28:29], v[42:43] op_sel_hi:[1,0]
	v_pk_mul_f32 v[26:27], v[26:27], v[42:43] op_sel_hi:[1,0]
	v_pk_mul_f32 v[12:13], v[12:13], v[42:43] op_sel_hi:[1,0]
	v_pk_mul_f32 v[10:11], v[10:11], v[42:43] op_sel_hi:[1,0]
	s_branch .LBB0_697
